# conv_fin (LayerNorm+swish) hand-written with batched loads; NSA masked edge tiles on the pipelined path; NSA gated-sum RMW batched
# speedup vs baseline: 1.0575x; 1.0039x over previous
.LBB0_297:
	ds_bpermute_b32 v0, v172, v66
	global_load_dword v67, v[124:125], off offset:8
	global_load_dwordx4 v[212:215], v[122:123], off
	global_load_dwordx4 v[216:219], v[122:123], off offset:32
	global_load_dwordx4 v[220:223], v[122:123], off offset:64
	global_load_dwordx4 v[224:227], v[122:123], off offset:96
	global_load_dwordx4 v[228:231], v[122:123], off offset:128
	global_load_dwordx4 v[232:235], v[122:123], off offset:160
	global_load_dwordx4 v[236:239], v[122:123], off offset:192
	global_load_dwordx4 v[240:243], v[122:123], off offset:224
	global_load_dwordx4 v[244:247], v[122:123], off offset:256
	global_load_dwordx4 v[248:251], v[122:123], off offset:288
	global_load_dwordx4 v[252:255], v[122:123], off offset:320
	global_load_dwordx4 v[196:199], v[122:123], off offset:352
	global_load_dwordx4 v[200:203], v[122:123], off offset:384
	global_load_dwordx4 v[204:207], v[122:123], off offset:416
	global_load_dwordx4 v[72:75], v[122:123], off offset:448
	global_load_dwordx4 v[76:79], v[122:123], off offset:480
	s_load_dwordx2 s[22:23], s[12:13], 0x178
	s_movk_i32 s66, 0x500
	s_waitcnt lgkmcnt(0)
	v_add_f32_e32 v0, v66, v0
	global_load_ushort v66, v[120:121], off offset:4
	v_cmp_lt_f32_e32 vcc, 0, v0
	v_rcp_f32_e32 v0, v0
	v_mov_b64_e32 v[68:69], s[22:23]
	v_mad_i64_i32 v[68:69], s[22:23], v114, s81, v[68:69]
	v_cndmask_b32_e32 v0, 0, v0, vcc
	s_movk_i32 s67, 0x7f
	v_readlane_b32 s72, v209, 40
	v_readlane_b32 s86, v209, 39
	s_movk_i32 s68, 0x480
	v_readlane_b32 s73, v209, 41
	s_waitcnt vmcnt(0)
	v_lshlrev_b32_e32 v66, 16, v66
	v_add_f32_e32 v66, v67, v66
	v_mul_f32_e32 v66, 0xbfb8aa3b, v66
	v_exp_f32_e32 v66, v66
	s_nop 0
	v_add_f32_e32 v66, 1.0, v66
	v_rcp_f32_e32 v66, v66
	s_nop 0
	v_mul_f32_e32 v66, v0, v66
	v_lshlrev_b32_e32 v0, 1, v116
	v_lshl_add_u64 v[68:69], v[68:69], 0, v[0:1]
	v_lshlrev_b32_e32 v0, 1, v115
	v_lshl_add_u64 v[68:69], v[68:69], 0, v[0:1]
	v_pk_fma_f32 v[212:213], v[50:51], v[66:67], v[212:213] op_sel_hi:[1,0,1]
	v_pk_fma_f32 v[214:215], v[52:53], v[66:67], v[214:215] op_sel_hi:[1,0,1]
	v_pk_fma_f32 v[216:217], v[54:55], v[66:67], v[216:217] op_sel_hi:[1,0,1]
	v_pk_fma_f32 v[218:219], v[56:57], v[66:67], v[218:219] op_sel_hi:[1,0,1]
	v_pk_fma_f32 v[220:221], v[58:59], v[66:67], v[220:221] op_sel_hi:[1,0,1]
	v_pk_fma_f32 v[222:223], v[60:61], v[66:67], v[222:223] op_sel_hi:[1,0,1]
	v_pk_fma_f32 v[224:225], v[62:63], v[66:67], v[224:225] op_sel_hi:[1,0,1]
	v_pk_fma_f32 v[226:227], v[64:65], v[66:67], v[226:227] op_sel_hi:[1,0,1]
	v_pk_fma_f32 v[228:229], v[34:35], v[66:67], v[228:229] op_sel_hi:[1,0,1]
	v_pk_fma_f32 v[230:231], v[36:37], v[66:67], v[230:231] op_sel_hi:[1,0,1]
	v_pk_fma_f32 v[232:233], v[38:39], v[66:67], v[232:233] op_sel_hi:[1,0,1]
	v_pk_fma_f32 v[234:235], v[40:41], v[66:67], v[234:235] op_sel_hi:[1,0,1]
	v_pk_fma_f32 v[236:237], v[42:43], v[66:67], v[236:237] op_sel_hi:[1,0,1]
	v_pk_fma_f32 v[238:239], v[44:45], v[66:67], v[238:239] op_sel_hi:[1,0,1]
	v_pk_fma_f32 v[240:241], v[46:47], v[66:67], v[240:241] op_sel_hi:[1,0,1]
	v_pk_fma_f32 v[242:243], v[48:49], v[66:67], v[242:243] op_sel_hi:[1,0,1]
	v_pk_fma_f32 v[244:245], v[18:19], v[66:67], v[244:245] op_sel_hi:[1,0,1]
	v_pk_fma_f32 v[246:247], v[20:21], v[66:67], v[246:247] op_sel_hi:[1,0,1]
	v_pk_fma_f32 v[248:249], v[22:23], v[66:67], v[248:249] op_sel_hi:[1,0,1]
	v_pk_fma_f32 v[250:251], v[24:25], v[66:67], v[250:251] op_sel_hi:[1,0,1]
	v_pk_fma_f32 v[252:253], v[26:27], v[66:67], v[252:253] op_sel_hi:[1,0,1]
	v_pk_fma_f32 v[254:255], v[28:29], v[66:67], v[254:255] op_sel_hi:[1,0,1]
	v_pk_fma_f32 v[196:197], v[30:31], v[66:67], v[196:197] op_sel_hi:[1,0,1]
	v_pk_fma_f32 v[198:199], v[32:33], v[66:67], v[198:199] op_sel_hi:[1,0,1]
	v_pk_fma_f32 v[200:201], v[2:3], v[66:67], v[200:201] op_sel_hi:[1,0,1]
	v_pk_fma_f32 v[202:203], v[4:5], v[66:67], v[202:203] op_sel_hi:[1,0,1]
	v_pk_fma_f32 v[204:205], v[6:7], v[66:67], v[204:205] op_sel_hi:[1,0,1]
	v_pk_fma_f32 v[206:207], v[8:9], v[66:67], v[206:207] op_sel_hi:[1,0,1]
	v_pk_fma_f32 v[72:73], v[10:11], v[66:67], v[72:73] op_sel_hi:[1,0,1]
	v_pk_fma_f32 v[74:75], v[12:13], v[66:67], v[74:75] op_sel_hi:[1,0,1]
	v_pk_fma_f32 v[76:77], v[14:15], v[66:67], v[76:77] op_sel_hi:[1,0,1]
	v_pk_fma_f32 v[78:79], v[16:17], v[66:67], v[78:79] op_sel_hi:[1,0,1]
	v_cvt_pk_bf16_f32 v212, v212, v213
	v_cvt_pk_bf16_f32 v213, v214, v215
	v_cvt_pk_bf16_f32 v216, v216, v217
	v_cvt_pk_bf16_f32 v217, v218, v219
	v_cvt_pk_bf16_f32 v220, v220, v221
	v_cvt_pk_bf16_f32 v221, v222, v223
	v_cvt_pk_bf16_f32 v224, v224, v225
	v_cvt_pk_bf16_f32 v225, v226, v227
	v_cvt_pk_bf16_f32 v228, v228, v229
	v_cvt_pk_bf16_f32 v229, v230, v231
	v_cvt_pk_bf16_f32 v232, v232, v233
	v_cvt_pk_bf16_f32 v233, v234, v235
	v_cvt_pk_bf16_f32 v236, v236, v237
	v_cvt_pk_bf16_f32 v237, v238, v239
	v_cvt_pk_bf16_f32 v240, v240, v241
	v_cvt_pk_bf16_f32 v241, v242, v243
	v_cvt_pk_bf16_f32 v244, v244, v245
	v_cvt_pk_bf16_f32 v245, v246, v247
	v_cvt_pk_bf16_f32 v248, v248, v249
	v_cvt_pk_bf16_f32 v249, v250, v251
	v_cvt_pk_bf16_f32 v252, v252, v253
	v_cvt_pk_bf16_f32 v253, v254, v255
	v_cvt_pk_bf16_f32 v196, v196, v197
	v_cvt_pk_bf16_f32 v197, v198, v199
	v_cvt_pk_bf16_f32 v200, v200, v201
	v_cvt_pk_bf16_f32 v201, v202, v203
	v_cvt_pk_bf16_f32 v204, v204, v205
	v_cvt_pk_bf16_f32 v205, v206, v207
	v_cvt_pk_bf16_f32 v72, v72, v73
	v_cvt_pk_bf16_f32 v73, v74, v75
	v_cvt_pk_bf16_f32 v76, v76, v77
	v_cvt_pk_bf16_f32 v77, v78, v79
	global_store_dwordx2 v[68:69], v[212:213], off
	global_store_dwordx2 v[68:69], v[216:217], off offset:16
	global_store_dwordx2 v[68:69], v[220:221], off offset:32
	global_store_dwordx2 v[68:69], v[224:225], off offset:48
	global_store_dwordx2 v[68:69], v[228:229], off offset:64
	global_store_dwordx2 v[68:69], v[232:233], off offset:80
	global_store_dwordx2 v[68:69], v[236:237], off offset:96
	global_store_dwordx2 v[68:69], v[240:241], off offset:112
	global_store_dwordx2 v[68:69], v[244:245], off offset:128
	global_store_dwordx2 v[68:69], v[248:249], off offset:144
	global_store_dwordx2 v[68:69], v[252:253], off offset:160
	global_store_dwordx2 v[68:69], v[196:197], off offset:176
	global_store_dwordx2 v[68:69], v[200:201], off offset:192
	global_store_dwordx2 v[68:69], v[204:205], off offset:208
	global_store_dwordx2 v[68:69], v[72:73], off offset:224
	global_store_dwordx2 v[68:69], v[76:77], off offset:240

.LBB0_299:
	s_cmpk_gt_i32 s21, 0x1ff
	s_mov_b64 s[40:41], -1
	s_movk_i32 s0, 0x4e
	s_cbranch_scc0 .LBB0_303
	s_load_dwordx4 s[28:31], s[12:13], 0x88
	s_load_dwordx2 s[40:41], s[12:13], 0x1d8
	s_load_dwordx2 s[24:25], s[12:13], 0x1c0
	s_load_dwordx2 s[22:23], s[12:13], 0x178
	v_lshlrev_b32_e32 v116, 4, v131
	v_lshlrev_b32_e32 v117, 3, v131
	s_lshl_b32 s42, s78, 3
	s_lshl_b32 s44, s78, 12
	s_mul_i32 s45, s78, 0x1080
	s_waitcnt lgkmcnt(0)
	global_load_dwordx4 v[98:101], v116, s[28:29]
	global_load_dwordx4 v[102:105], v116, s[30:31]
	s_add_u32 s42, s40, s42
	s_addc_u32 s43, s41, 0
	global_load_dwordx2 v[2:3], v1, s[42:43]
	global_load_dwordx2 v[4:5], v1, s[42:43] offset:8
	global_load_dwordx2 v[6:7], v1, s[42:43] offset:16
	global_load_dwordx2 v[8:9], v1, s[42:43] offset:24
	global_load_dwordx2 v[10:11], v1, s[42:43] offset:32
	global_load_dwordx2 v[12:13], v1, s[42:43] offset:40
	global_load_dwordx2 v[14:15], v1, s[42:43] offset:48
	global_load_dwordx2 v[16:17], v1, s[42:43] offset:56
	global_load_dwordx2 v[18:19], v1, s[42:43] offset:64
	global_load_dwordx2 v[20:21], v1, s[42:43] offset:72
	global_load_dwordx2 v[22:23], v1, s[42:43] offset:80
	global_load_dwordx2 v[24:25], v1, s[42:43] offset:88
	global_load_dwordx2 v[26:27], v1, s[42:43] offset:96
	global_load_dwordx2 v[28:29], v1, s[42:43] offset:104
	global_load_dwordx2 v[30:31], v1, s[42:43] offset:112
	global_load_dwordx2 v[32:33], v1, s[42:43] offset:120
	s_add_u32 s24, s24, s44
	s_addc_u32 s25, s25, 0
	global_load_dwordx4 v[34:37], v116, s[24:25]
	s_add_u32 s24, s24, 0x1000
	s_addc_u32 s25, s25, 0
	global_load_dwordx4 v[38:41], v116, s[24:25]
	s_add_u32 s24, s24, 0x1000
	s_addc_u32 s25, s25, 0
	global_load_dwordx4 v[42:45], v116, s[24:25]
	s_add_u32 s24, s24, 0x1000
	s_addc_u32 s25, s25, 0
	global_load_dwordx4 v[46:49], v116, s[24:25]
	s_add_u32 s24, s24, 0x1000
	s_addc_u32 s25, s25, 0
	global_load_dwordx4 v[50:53], v116, s[24:25]
	s_add_u32 s24, s24, 0x1000
	s_addc_u32 s25, s25, 0
	global_load_dwordx4 v[54:57], v116, s[24:25]
	s_add_u32 s24, s24, 0x1000
	s_addc_u32 s25, s25, 0
	global_load_dwordx4 v[58:61], v116, s[24:25]
	s_add_u32 s24, s24, 0x1000
	s_addc_u32 s25, s25, 0
	global_load_dwordx4 v[62:65], v116, s[24:25]
	s_add_u32 s24, s24, 0x1000
	s_addc_u32 s25, s25, 0
	global_load_dwordx4 v[66:69], v116, s[24:25]
	s_add_u32 s24, s24, 0x1000
	s_addc_u32 s25, s25, 0
	global_load_dwordx4 v[70:73], v116, s[24:25]
	s_add_u32 s24, s24, 0x1000
	s_addc_u32 s25, s25, 0
	global_load_dwordx4 v[74:77], v116, s[24:25]
	s_add_u32 s24, s24, 0x1000
	s_addc_u32 s25, s25, 0
	global_load_dwordx4 v[78:81], v116, s[24:25]
	s_add_u32 s24, s24, 0x1000
	s_addc_u32 s25, s25, 0
	global_load_dwordx4 v[82:85], v116, s[24:25]
	s_add_u32 s24, s24, 0x1000
	s_addc_u32 s25, s25, 0
	global_load_dwordx4 v[86:89], v116, s[24:25]
	s_add_u32 s24, s24, 0x1000
	s_addc_u32 s25, s25, 0
	global_load_dwordx4 v[90:93], v116, s[24:25]
	s_add_u32 s24, s24, 0x1000
	s_addc_u32 s25, s25, 0
	global_load_dwordx4 v[94:97], v116, s[24:25]
	s_add_u32 s22, s22, s45
	s_addc_u32 s23, s23, 0
	s_waitcnt vmcnt(16)
	v_mul_f32_e32 v2, 0x3a800000, v2
	v_mul_f32_e32 v3, 0x3a800000, v3
	v_mul_f32_e32 v4, 0x3a800000, v4
	v_mul_f32_e32 v5, 0x3a800000, v5
	v_mul_f32_e32 v6, 0x3a800000, v6
	v_mul_f32_e32 v7, 0x3a800000, v7
	v_mul_f32_e32 v8, 0x3a800000, v8
	v_mul_f32_e32 v9, 0x3a800000, v9
	v_mul_f32_e32 v10, 0x3a800000, v10
	v_mul_f32_e32 v11, 0x3a800000, v11
	v_mul_f32_e32 v12, 0x3a800000, v12
	v_mul_f32_e32 v13, 0x3a800000, v13
	v_mul_f32_e32 v14, 0x3a800000, v14
	v_mul_f32_e32 v15, 0x3a800000, v15
	v_mul_f32_e32 v16, 0x3a800000, v16
	v_mul_f32_e32 v17, 0x3a800000, v17
	v_mul_f32_e32 v18, 0x3a800000, v18
	v_mul_f32_e32 v19, 0x3a800000, v19
	v_mul_f32_e32 v20, 0x3a800000, v20
	v_mul_f32_e32 v21, 0x3a800000, v21
	v_mul_f32_e32 v22, 0x3a800000, v22
	v_mul_f32_e32 v23, 0x3a800000, v23
	v_mul_f32_e32 v24, 0x3a800000, v24
	v_mul_f32_e32 v25, 0x3a800000, v25
	v_mul_f32_e32 v26, 0x3a800000, v26
	v_mul_f32_e32 v27, 0x3a800000, v27
	v_mul_f32_e32 v28, 0x3a800000, v28
	v_mul_f32_e32 v29, 0x3a800000, v29
	v_mul_f32_e32 v30, 0x3a800000, v30
	v_mul_f32_e32 v31, 0x3a800000, v31
	v_mul_f32_e32 v32, 0x3a800000, v32
	v_mul_f32_e32 v33, 0x3a800000, v33
	v_fma_f32 v3, -v2, v2, v3
	v_fma_f32 v5, -v4, v4, v5
	v_fma_f32 v7, -v6, v6, v7
	v_fma_f32 v9, -v8, v8, v9
	v_fma_f32 v11, -v10, v10, v11
	v_fma_f32 v13, -v12, v12, v13
	v_fma_f32 v15, -v14, v14, v15
	v_fma_f32 v17, -v16, v16, v17
	v_fma_f32 v19, -v18, v18, v19
	v_fma_f32 v21, -v20, v20, v21
	v_fma_f32 v23, -v22, v22, v23
	v_fma_f32 v25, -v24, v24, v25
	v_fma_f32 v27, -v26, v26, v27
	v_fma_f32 v29, -v28, v28, v29
	v_fma_f32 v31, -v30, v30, v31
	v_fma_f32 v33, -v32, v32, v33
	v_max_f32_e32 v3, 0, v3
	v_max_f32_e32 v5, 0, v5
	v_max_f32_e32 v7, 0, v7
	v_max_f32_e32 v9, 0, v9
	v_max_f32_e32 v11, 0, v11
	v_max_f32_e32 v13, 0, v13
	v_max_f32_e32 v15, 0, v15
	v_max_f32_e32 v17, 0, v17
	v_max_f32_e32 v19, 0, v19
	v_max_f32_e32 v21, 0, v21
	v_max_f32_e32 v23, 0, v23
	v_max_f32_e32 v25, 0, v25
	v_max_f32_e32 v27, 0, v27
	v_max_f32_e32 v29, 0, v29
	v_max_f32_e32 v31, 0, v31
	v_max_f32_e32 v33, 0, v33
	v_add_f32_e32 v3, 0x3727c5ac, v3
	v_add_f32_e32 v5, 0x3727c5ac, v5
	v_add_f32_e32 v7, 0x3727c5ac, v7
	v_add_f32_e32 v9, 0x3727c5ac, v9
	v_add_f32_e32 v11, 0x3727c5ac, v11
	v_add_f32_e32 v13, 0x3727c5ac, v13
	v_add_f32_e32 v15, 0x3727c5ac, v15
	v_add_f32_e32 v17, 0x3727c5ac, v17
	v_add_f32_e32 v19, 0x3727c5ac, v19
	v_add_f32_e32 v21, 0x3727c5ac, v21
	v_add_f32_e32 v23, 0x3727c5ac, v23
	v_add_f32_e32 v25, 0x3727c5ac, v25
	v_add_f32_e32 v27, 0x3727c5ac, v27
	v_add_f32_e32 v29, 0x3727c5ac, v29
	v_add_f32_e32 v31, 0x3727c5ac, v31
	v_add_f32_e32 v33, 0x3727c5ac, v33
	v_rsq_f32_e32 v3, v3
	v_rsq_f32_e32 v5, v5
	v_rsq_f32_e32 v7, v7
	v_rsq_f32_e32 v9, v9
	v_rsq_f32_e32 v11, v11
	v_rsq_f32_e32 v13, v13
	v_rsq_f32_e32 v15, v15
	v_rsq_f32_e32 v17, v17
	v_rsq_f32_e32 v19, v19
	v_rsq_f32_e32 v21, v21
	v_rsq_f32_e32 v23, v23
	v_rsq_f32_e32 v25, v25
	v_rsq_f32_e32 v27, v27
	v_rsq_f32_e32 v29, v29
	v_rsq_f32_e32 v31, v31
	v_rsq_f32_e32 v33, v33
	s_waitcnt vmcnt(15)
	v_sub_f32_e32 v34, v34, v2
	v_sub_f32_e32 v35, v35, v2
	v_sub_f32_e32 v36, v36, v2
	v_sub_f32_e32 v37, v37, v2
	v_mul_f32_e32 v34, v34, v3
	v_mul_f32_e32 v35, v35, v3
	v_mul_f32_e32 v36, v36, v3
	v_mul_f32_e32 v37, v37, v3
	v_fma_f32 v34, v34, v98, v102
	v_fma_f32 v35, v35, v99, v103
	v_fma_f32 v36, v36, v100, v104
	v_fma_f32 v37, v37, v101, v105
	v_mul_f32_e32 v106, 0xbfb8aa3b, v34
	v_mul_f32_e32 v107, 0xbfb8aa3b, v35
	v_mul_f32_e32 v108, 0xbfb8aa3b, v36
	v_mul_f32_e32 v109, 0xbfb8aa3b, v37
	v_exp_f32_e32 v106, v106
	v_exp_f32_e32 v107, v107
	v_exp_f32_e32 v108, v108
	v_exp_f32_e32 v109, v109
	v_add_f32_e32 v106, 1.0, v106
	v_add_f32_e32 v107, 1.0, v107
	v_add_f32_e32 v108, 1.0, v108
	v_add_f32_e32 v109, 1.0, v109
	v_rcp_f32_e32 v106, v106
	v_rcp_f32_e32 v107, v107
	v_rcp_f32_e32 v108, v108
	v_rcp_f32_e32 v109, v109
	v_mul_f32_e32 v34, v34, v106
	v_mul_f32_e32 v35, v35, v107
	v_mul_f32_e32 v36, v36, v108
	v_mul_f32_e32 v37, v37, v109
	v_cvt_pk_bf16_f32 v34, v34, v35
	v_cvt_pk_bf16_f32 v35, v36, v37
	s_waitcnt vmcnt(14)
	v_sub_f32_e32 v38, v38, v4
	v_sub_f32_e32 v39, v39, v4
	v_sub_f32_e32 v40, v40, v4
	v_sub_f32_e32 v41, v41, v4
	v_mul_f32_e32 v38, v38, v5
	v_mul_f32_e32 v39, v39, v5
	v_mul_f32_e32 v40, v40, v5
	v_mul_f32_e32 v41, v41, v5
	v_fma_f32 v38, v38, v98, v102
	v_fma_f32 v39, v39, v99, v103
	v_fma_f32 v40, v40, v100, v104
	v_fma_f32 v41, v41, v101, v105
	v_mul_f32_e32 v106, 0xbfb8aa3b, v38
	v_mul_f32_e32 v107, 0xbfb8aa3b, v39
	v_mul_f32_e32 v108, 0xbfb8aa3b, v40
	v_mul_f32_e32 v109, 0xbfb8aa3b, v41
	v_exp_f32_e32 v106, v106
	v_exp_f32_e32 v107, v107
	v_exp_f32_e32 v108, v108
	v_exp_f32_e32 v109, v109
	v_add_f32_e32 v106, 1.0, v106
	v_add_f32_e32 v107, 1.0, v107
	v_add_f32_e32 v108, 1.0, v108
	v_add_f32_e32 v109, 1.0, v109
	v_rcp_f32_e32 v106, v106
	v_rcp_f32_e32 v107, v107
	v_rcp_f32_e32 v108, v108
	v_rcp_f32_e32 v109, v109
	v_mul_f32_e32 v38, v38, v106
	v_mul_f32_e32 v39, v39, v107
	v_mul_f32_e32 v40, v40, v108
	v_mul_f32_e32 v41, v41, v109
	v_cvt_pk_bf16_f32 v38, v38, v39
	v_cvt_pk_bf16_f32 v39, v40, v41
	s_waitcnt vmcnt(13)
	v_sub_f32_e32 v42, v42, v6
	v_sub_f32_e32 v43, v43, v6
	v_sub_f32_e32 v44, v44, v6
	v_sub_f32_e32 v45, v45, v6
	v_mul_f32_e32 v42, v42, v7
	v_mul_f32_e32 v43, v43, v7
	v_mul_f32_e32 v44, v44, v7
	v_mul_f32_e32 v45, v45, v7
	v_fma_f32 v42, v42, v98, v102
	v_fma_f32 v43, v43, v99, v103
	v_fma_f32 v44, v44, v100, v104
	v_fma_f32 v45, v45, v101, v105
	v_mul_f32_e32 v106, 0xbfb8aa3b, v42
	v_mul_f32_e32 v107, 0xbfb8aa3b, v43
	v_mul_f32_e32 v108, 0xbfb8aa3b, v44
	v_mul_f32_e32 v109, 0xbfb8aa3b, v45
	v_exp_f32_e32 v106, v106
	v_exp_f32_e32 v107, v107
	v_exp_f32_e32 v108, v108
	v_exp_f32_e32 v109, v109
	v_add_f32_e32 v106, 1.0, v106
	v_add_f32_e32 v107, 1.0, v107
	v_add_f32_e32 v108, 1.0, v108
	v_add_f32_e32 v109, 1.0, v109
	v_rcp_f32_e32 v106, v106
	v_rcp_f32_e32 v107, v107
	v_rcp_f32_e32 v108, v108
	v_rcp_f32_e32 v109, v109
	v_mul_f32_e32 v42, v42, v106
	v_mul_f32_e32 v43, v43, v107
	v_mul_f32_e32 v44, v44, v108
	v_mul_f32_e32 v45, v45, v109
	v_cvt_pk_bf16_f32 v42, v42, v43
	v_cvt_pk_bf16_f32 v43, v44, v45
	s_waitcnt vmcnt(12)
	v_sub_f32_e32 v46, v46, v8
	v_sub_f32_e32 v47, v47, v8
	v_sub_f32_e32 v48, v48, v8
	v_sub_f32_e32 v49, v49, v8
	v_mul_f32_e32 v46, v46, v9
	v_mul_f32_e32 v47, v47, v9
	v_mul_f32_e32 v48, v48, v9
	v_mul_f32_e32 v49, v49, v9
	v_fma_f32 v46, v46, v98, v102
	v_fma_f32 v47, v47, v99, v103
	v_fma_f32 v48, v48, v100, v104
	v_fma_f32 v49, v49, v101, v105
	v_mul_f32_e32 v106, 0xbfb8aa3b, v46
	v_mul_f32_e32 v107, 0xbfb8aa3b, v47
	v_mul_f32_e32 v108, 0xbfb8aa3b, v48
	v_mul_f32_e32 v109, 0xbfb8aa3b, v49
	v_exp_f32_e32 v106, v106
	v_exp_f32_e32 v107, v107
	v_exp_f32_e32 v108, v108
	v_exp_f32_e32 v109, v109
	v_add_f32_e32 v106, 1.0, v106
	v_add_f32_e32 v107, 1.0, v107
	v_add_f32_e32 v108, 1.0, v108
	v_add_f32_e32 v109, 1.0, v109
	v_rcp_f32_e32 v106, v106
	v_rcp_f32_e32 v107, v107
	v_rcp_f32_e32 v108, v108
	v_rcp_f32_e32 v109, v109
	v_mul_f32_e32 v46, v46, v106
	v_mul_f32_e32 v47, v47, v107
	v_mul_f32_e32 v48, v48, v108
	v_mul_f32_e32 v49, v49, v109
	v_cvt_pk_bf16_f32 v46, v46, v47
	v_cvt_pk_bf16_f32 v47, v48, v49
	s_waitcnt vmcnt(11)
	v_sub_f32_e32 v50, v50, v10
	v_sub_f32_e32 v51, v51, v10
	v_sub_f32_e32 v52, v52, v10
	v_sub_f32_e32 v53, v53, v10
	v_mul_f32_e32 v50, v50, v11
	v_mul_f32_e32 v51, v51, v11
	v_mul_f32_e32 v52, v52, v11
	v_mul_f32_e32 v53, v53, v11
	v_fma_f32 v50, v50, v98, v102
	v_fma_f32 v51, v51, v99, v103
	v_fma_f32 v52, v52, v100, v104
	v_fma_f32 v53, v53, v101, v105
	v_mul_f32_e32 v106, 0xbfb8aa3b, v50
	v_mul_f32_e32 v107, 0xbfb8aa3b, v51
	v_mul_f32_e32 v108, 0xbfb8aa3b, v52
	v_mul_f32_e32 v109, 0xbfb8aa3b, v53
	v_exp_f32_e32 v106, v106
	v_exp_f32_e32 v107, v107
	v_exp_f32_e32 v108, v108
	v_exp_f32_e32 v109, v109
	v_add_f32_e32 v106, 1.0, v106
	v_add_f32_e32 v107, 1.0, v107
	v_add_f32_e32 v108, 1.0, v108
	v_add_f32_e32 v109, 1.0, v109
	v_rcp_f32_e32 v106, v106
	v_rcp_f32_e32 v107, v107
	v_rcp_f32_e32 v108, v108
	v_rcp_f32_e32 v109, v109
	v_mul_f32_e32 v50, v50, v106
	v_mul_f32_e32 v51, v51, v107
	v_mul_f32_e32 v52, v52, v108
	v_mul_f32_e32 v53, v53, v109
	v_cvt_pk_bf16_f32 v50, v50, v51
	v_cvt_pk_bf16_f32 v51, v52, v53
	s_waitcnt vmcnt(10)
	v_sub_f32_e32 v54, v54, v12
	v_sub_f32_e32 v55, v55, v12
	v_sub_f32_e32 v56, v56, v12
	v_sub_f32_e32 v57, v57, v12
	v_mul_f32_e32 v54, v54, v13
	v_mul_f32_e32 v55, v55, v13
	v_mul_f32_e32 v56, v56, v13
	v_mul_f32_e32 v57, v57, v13
	v_fma_f32 v54, v54, v98, v102
	v_fma_f32 v55, v55, v99, v103
	v_fma_f32 v56, v56, v100, v104
	v_fma_f32 v57, v57, v101, v105
	v_mul_f32_e32 v106, 0xbfb8aa3b, v54
	v_mul_f32_e32 v107, 0xbfb8aa3b, v55
	v_mul_f32_e32 v108, 0xbfb8aa3b, v56
	v_mul_f32_e32 v109, 0xbfb8aa3b, v57
	v_exp_f32_e32 v106, v106
	v_exp_f32_e32 v107, v107
	v_exp_f32_e32 v108, v108
	v_exp_f32_e32 v109, v109
	v_add_f32_e32 v106, 1.0, v106
	v_add_f32_e32 v107, 1.0, v107
	v_add_f32_e32 v108, 1.0, v108
	v_add_f32_e32 v109, 1.0, v109
	v_rcp_f32_e32 v106, v106
	v_rcp_f32_e32 v107, v107
	v_rcp_f32_e32 v108, v108
	v_rcp_f32_e32 v109, v109
	v_mul_f32_e32 v54, v54, v106
	v_mul_f32_e32 v55, v55, v107
	v_mul_f32_e32 v56, v56, v108
	v_mul_f32_e32 v57, v57, v109
	v_cvt_pk_bf16_f32 v54, v54, v55
	v_cvt_pk_bf16_f32 v55, v56, v57
	s_waitcnt vmcnt(9)
	v_sub_f32_e32 v58, v58, v14
	v_sub_f32_e32 v59, v59, v14
	v_sub_f32_e32 v60, v60, v14
	v_sub_f32_e32 v61, v61, v14
	v_mul_f32_e32 v58, v58, v15
	v_mul_f32_e32 v59, v59, v15
	v_mul_f32_e32 v60, v60, v15
	v_mul_f32_e32 v61, v61, v15
	v_fma_f32 v58, v58, v98, v102
	v_fma_f32 v59, v59, v99, v103
	v_fma_f32 v60, v60, v100, v104
	v_fma_f32 v61, v61, v101, v105
	v_mul_f32_e32 v106, 0xbfb8aa3b, v58
	v_mul_f32_e32 v107, 0xbfb8aa3b, v59
	v_mul_f32_e32 v108, 0xbfb8aa3b, v60
	v_mul_f32_e32 v109, 0xbfb8aa3b, v61
	v_exp_f32_e32 v106, v106
	v_exp_f32_e32 v107, v107
	v_exp_f32_e32 v108, v108
	v_exp_f32_e32 v109, v109
	v_add_f32_e32 v106, 1.0, v106
	v_add_f32_e32 v107, 1.0, v107
	v_add_f32_e32 v108, 1.0, v108
	v_add_f32_e32 v109, 1.0, v109
	v_rcp_f32_e32 v106, v106
	v_rcp_f32_e32 v107, v107
	v_rcp_f32_e32 v108, v108
	v_rcp_f32_e32 v109, v109
	v_mul_f32_e32 v58, v58, v106
	v_mul_f32_e32 v59, v59, v107
	v_mul_f32_e32 v60, v60, v108
	v_mul_f32_e32 v61, v61, v109
	v_cvt_pk_bf16_f32 v58, v58, v59
	v_cvt_pk_bf16_f32 v59, v60, v61
	s_waitcnt vmcnt(8)
	v_sub_f32_e32 v62, v62, v16
	v_sub_f32_e32 v63, v63, v16
	v_sub_f32_e32 v64, v64, v16
	v_sub_f32_e32 v65, v65, v16
	v_mul_f32_e32 v62, v62, v17
	v_mul_f32_e32 v63, v63, v17
	v_mul_f32_e32 v64, v64, v17
	v_mul_f32_e32 v65, v65, v17
	v_fma_f32 v62, v62, v98, v102
	v_fma_f32 v63, v63, v99, v103
	v_fma_f32 v64, v64, v100, v104
	v_fma_f32 v65, v65, v101, v105
	v_mul_f32_e32 v106, 0xbfb8aa3b, v62
	v_mul_f32_e32 v107, 0xbfb8aa3b, v63
	v_mul_f32_e32 v108, 0xbfb8aa3b, v64
	v_mul_f32_e32 v109, 0xbfb8aa3b, v65
	v_exp_f32_e32 v106, v106
	v_exp_f32_e32 v107, v107
	v_exp_f32_e32 v108, v108
	v_exp_f32_e32 v109, v109
	v_add_f32_e32 v106, 1.0, v106
	v_add_f32_e32 v107, 1.0, v107
	v_add_f32_e32 v108, 1.0, v108
	v_add_f32_e32 v109, 1.0, v109
	v_rcp_f32_e32 v106, v106
	v_rcp_f32_e32 v107, v107
	v_rcp_f32_e32 v108, v108
	v_rcp_f32_e32 v109, v109
	v_mul_f32_e32 v62, v62, v106
	v_mul_f32_e32 v63, v63, v107
	v_mul_f32_e32 v64, v64, v108
	v_mul_f32_e32 v65, v65, v109
	v_cvt_pk_bf16_f32 v62, v62, v63
	v_cvt_pk_bf16_f32 v63, v64, v65
	s_waitcnt vmcnt(7)
	v_sub_f32_e32 v66, v66, v18
	v_sub_f32_e32 v67, v67, v18
	v_sub_f32_e32 v68, v68, v18
	v_sub_f32_e32 v69, v69, v18
	v_mul_f32_e32 v66, v66, v19
	v_mul_f32_e32 v67, v67, v19
	v_mul_f32_e32 v68, v68, v19
	v_mul_f32_e32 v69, v69, v19
	v_fma_f32 v66, v66, v98, v102
	v_fma_f32 v67, v67, v99, v103
	v_fma_f32 v68, v68, v100, v104
	v_fma_f32 v69, v69, v101, v105
	v_mul_f32_e32 v106, 0xbfb8aa3b, v66
	v_mul_f32_e32 v107, 0xbfb8aa3b, v67
	v_mul_f32_e32 v108, 0xbfb8aa3b, v68
	v_mul_f32_e32 v109, 0xbfb8aa3b, v69
	v_exp_f32_e32 v106, v106
	v_exp_f32_e32 v107, v107
	v_exp_f32_e32 v108, v108
	v_exp_f32_e32 v109, v109
	v_add_f32_e32 v106, 1.0, v106
	v_add_f32_e32 v107, 1.0, v107
	v_add_f32_e32 v108, 1.0, v108
	v_add_f32_e32 v109, 1.0, v109
	v_rcp_f32_e32 v106, v106
	v_rcp_f32_e32 v107, v107
	v_rcp_f32_e32 v108, v108
	v_rcp_f32_e32 v109, v109
	v_mul_f32_e32 v66, v66, v106
	v_mul_f32_e32 v67, v67, v107
	v_mul_f32_e32 v68, v68, v108
	v_mul_f32_e32 v69, v69, v109
	v_cvt_pk_bf16_f32 v66, v66, v67
	v_cvt_pk_bf16_f32 v67, v68, v69
	s_waitcnt vmcnt(6)
	v_sub_f32_e32 v70, v70, v20
	v_sub_f32_e32 v71, v71, v20
	v_sub_f32_e32 v72, v72, v20
	v_sub_f32_e32 v73, v73, v20
	v_mul_f32_e32 v70, v70, v21
	v_mul_f32_e32 v71, v71, v21
	v_mul_f32_e32 v72, v72, v21
	v_mul_f32_e32 v73, v73, v21
	v_fma_f32 v70, v70, v98, v102
	v_fma_f32 v71, v71, v99, v103
	v_fma_f32 v72, v72, v100, v104
	v_fma_f32 v73, v73, v101, v105
	v_mul_f32_e32 v106, 0xbfb8aa3b, v70
	v_mul_f32_e32 v107, 0xbfb8aa3b, v71
	v_mul_f32_e32 v108, 0xbfb8aa3b, v72
	v_mul_f32_e32 v109, 0xbfb8aa3b, v73
	v_exp_f32_e32 v106, v106
	v_exp_f32_e32 v107, v107
	v_exp_f32_e32 v108, v108
	v_exp_f32_e32 v109, v109
	v_add_f32_e32 v106, 1.0, v106
	v_add_f32_e32 v107, 1.0, v107
	v_add_f32_e32 v108, 1.0, v108
	v_add_f32_e32 v109, 1.0, v109
	v_rcp_f32_e32 v106, v106
	v_rcp_f32_e32 v107, v107
	v_rcp_f32_e32 v108, v108
	v_rcp_f32_e32 v109, v109
	v_mul_f32_e32 v70, v70, v106
	v_mul_f32_e32 v71, v71, v107
	v_mul_f32_e32 v72, v72, v108
	v_mul_f32_e32 v73, v73, v109
	v_cvt_pk_bf16_f32 v70, v70, v71
	v_cvt_pk_bf16_f32 v71, v72, v73
	s_waitcnt vmcnt(5)
	v_sub_f32_e32 v74, v74, v22
	v_sub_f32_e32 v75, v75, v22
	v_sub_f32_e32 v76, v76, v22
	v_sub_f32_e32 v77, v77, v22
	v_mul_f32_e32 v74, v74, v23
	v_mul_f32_e32 v75, v75, v23
	v_mul_f32_e32 v76, v76, v23
	v_mul_f32_e32 v77, v77, v23
	v_fma_f32 v74, v74, v98, v102
	v_fma_f32 v75, v75, v99, v103
	v_fma_f32 v76, v76, v100, v104
	v_fma_f32 v77, v77, v101, v105
	v_mul_f32_e32 v106, 0xbfb8aa3b, v74
	v_mul_f32_e32 v107, 0xbfb8aa3b, v75
	v_mul_f32_e32 v108, 0xbfb8aa3b, v76
	v_mul_f32_e32 v109, 0xbfb8aa3b, v77
	v_exp_f32_e32 v106, v106
	v_exp_f32_e32 v107, v107
	v_exp_f32_e32 v108, v108
	v_exp_f32_e32 v109, v109
	v_add_f32_e32 v106, 1.0, v106
	v_add_f32_e32 v107, 1.0, v107
	v_add_f32_e32 v108, 1.0, v108
	v_add_f32_e32 v109, 1.0, v109
	v_rcp_f32_e32 v106, v106
	v_rcp_f32_e32 v107, v107
	v_rcp_f32_e32 v108, v108
	v_rcp_f32_e32 v109, v109
	v_mul_f32_e32 v74, v74, v106
	v_mul_f32_e32 v75, v75, v107
	v_mul_f32_e32 v76, v76, v108
	v_mul_f32_e32 v77, v77, v109
	v_cvt_pk_bf16_f32 v74, v74, v75
	v_cvt_pk_bf16_f32 v75, v76, v77
	s_waitcnt vmcnt(4)
	v_sub_f32_e32 v78, v78, v24
	v_sub_f32_e32 v79, v79, v24
	v_sub_f32_e32 v80, v80, v24
	v_sub_f32_e32 v81, v81, v24
	v_mul_f32_e32 v78, v78, v25
	v_mul_f32_e32 v79, v79, v25
	v_mul_f32_e32 v80, v80, v25
	v_mul_f32_e32 v81, v81, v25
	v_fma_f32 v78, v78, v98, v102
	v_fma_f32 v79, v79, v99, v103
	v_fma_f32 v80, v80, v100, v104
	v_fma_f32 v81, v81, v101, v105
	v_mul_f32_e32 v106, 0xbfb8aa3b, v78
	v_mul_f32_e32 v107, 0xbfb8aa3b, v79
	v_mul_f32_e32 v108, 0xbfb8aa3b, v80
	v_mul_f32_e32 v109, 0xbfb8aa3b, v81
	v_exp_f32_e32 v106, v106
	v_exp_f32_e32 v107, v107
	v_exp_f32_e32 v108, v108
	v_exp_f32_e32 v109, v109
	v_add_f32_e32 v106, 1.0, v106
	v_add_f32_e32 v107, 1.0, v107
	v_add_f32_e32 v108, 1.0, v108
	v_add_f32_e32 v109, 1.0, v109
	v_rcp_f32_e32 v106, v106
	v_rcp_f32_e32 v107, v107
	v_rcp_f32_e32 v108, v108
	v_rcp_f32_e32 v109, v109
	v_mul_f32_e32 v78, v78, v106
	v_mul_f32_e32 v79, v79, v107
	v_mul_f32_e32 v80, v80, v108
	v_mul_f32_e32 v81, v81, v109
	v_cvt_pk_bf16_f32 v78, v78, v79
	v_cvt_pk_bf16_f32 v79, v80, v81
	s_waitcnt vmcnt(3)
	v_sub_f32_e32 v82, v82, v26
	v_sub_f32_e32 v83, v83, v26
	v_sub_f32_e32 v84, v84, v26
	v_sub_f32_e32 v85, v85, v26
	v_mul_f32_e32 v82, v82, v27
	v_mul_f32_e32 v83, v83, v27
	v_mul_f32_e32 v84, v84, v27
	v_mul_f32_e32 v85, v85, v27
	v_fma_f32 v82, v82, v98, v102
	v_fma_f32 v83, v83, v99, v103
	v_fma_f32 v84, v84, v100, v104
	v_fma_f32 v85, v85, v101, v105
	v_mul_f32_e32 v106, 0xbfb8aa3b, v82
	v_mul_f32_e32 v107, 0xbfb8aa3b, v83
	v_mul_f32_e32 v108, 0xbfb8aa3b, v84
	v_mul_f32_e32 v109, 0xbfb8aa3b, v85
	v_exp_f32_e32 v106, v106
	v_exp_f32_e32 v107, v107
	v_exp_f32_e32 v108, v108
	v_exp_f32_e32 v109, v109
	v_add_f32_e32 v106, 1.0, v106
	v_add_f32_e32 v107, 1.0, v107
	v_add_f32_e32 v108, 1.0, v108
	v_add_f32_e32 v109, 1.0, v109
	v_rcp_f32_e32 v106, v106
	v_rcp_f32_e32 v107, v107
	v_rcp_f32_e32 v108, v108
	v_rcp_f32_e32 v109, v109
	v_mul_f32_e32 v82, v82, v106
	v_mul_f32_e32 v83, v83, v107
	v_mul_f32_e32 v84, v84, v108
	v_mul_f32_e32 v85, v85, v109
	v_cvt_pk_bf16_f32 v82, v82, v83
	v_cvt_pk_bf16_f32 v83, v84, v85
	s_waitcnt vmcnt(2)
	v_sub_f32_e32 v86, v86, v28
	v_sub_f32_e32 v87, v87, v28
	v_sub_f32_e32 v88, v88, v28
	v_sub_f32_e32 v89, v89, v28
	v_mul_f32_e32 v86, v86, v29
	v_mul_f32_e32 v87, v87, v29
	v_mul_f32_e32 v88, v88, v29
	v_mul_f32_e32 v89, v89, v29
	v_fma_f32 v86, v86, v98, v102
	v_fma_f32 v87, v87, v99, v103
	v_fma_f32 v88, v88, v100, v104
	v_fma_f32 v89, v89, v101, v105
	v_mul_f32_e32 v106, 0xbfb8aa3b, v86
	v_mul_f32_e32 v107, 0xbfb8aa3b, v87
	v_mul_f32_e32 v108, 0xbfb8aa3b, v88
	v_mul_f32_e32 v109, 0xbfb8aa3b, v89
	v_exp_f32_e32 v106, v106
	v_exp_f32_e32 v107, v107
	v_exp_f32_e32 v108, v108
	v_exp_f32_e32 v109, v109
	v_add_f32_e32 v106, 1.0, v106
	v_add_f32_e32 v107, 1.0, v107
	v_add_f32_e32 v108, 1.0, v108
	v_add_f32_e32 v109, 1.0, v109
	v_rcp_f32_e32 v106, v106
	v_rcp_f32_e32 v107, v107
	v_rcp_f32_e32 v108, v108
	v_rcp_f32_e32 v109, v109
	v_mul_f32_e32 v86, v86, v106
	v_mul_f32_e32 v87, v87, v107
	v_mul_f32_e32 v88, v88, v108
	v_mul_f32_e32 v89, v89, v109
	v_cvt_pk_bf16_f32 v86, v86, v87
	v_cvt_pk_bf16_f32 v87, v88, v89
	s_waitcnt vmcnt(1)
	v_sub_f32_e32 v90, v90, v30
	v_sub_f32_e32 v91, v91, v30
	v_sub_f32_e32 v92, v92, v30
	v_sub_f32_e32 v93, v93, v30
	v_mul_f32_e32 v90, v90, v31
	v_mul_f32_e32 v91, v91, v31
	v_mul_f32_e32 v92, v92, v31
	v_mul_f32_e32 v93, v93, v31
	v_fma_f32 v90, v90, v98, v102
	v_fma_f32 v91, v91, v99, v103
	v_fma_f32 v92, v92, v100, v104
	v_fma_f32 v93, v93, v101, v105
	v_mul_f32_e32 v106, 0xbfb8aa3b, v90
	v_mul_f32_e32 v107, 0xbfb8aa3b, v91
	v_mul_f32_e32 v108, 0xbfb8aa3b, v92
	v_mul_f32_e32 v109, 0xbfb8aa3b, v93
	v_exp_f32_e32 v106, v106
	v_exp_f32_e32 v107, v107
	v_exp_f32_e32 v108, v108
	v_exp_f32_e32 v109, v109
	v_add_f32_e32 v106, 1.0, v106
	v_add_f32_e32 v107, 1.0, v107
	v_add_f32_e32 v108, 1.0, v108
	v_add_f32_e32 v109, 1.0, v109
	v_rcp_f32_e32 v106, v106
	v_rcp_f32_e32 v107, v107
	v_rcp_f32_e32 v108, v108
	v_rcp_f32_e32 v109, v109
	v_mul_f32_e32 v90, v90, v106
	v_mul_f32_e32 v91, v91, v107
	v_mul_f32_e32 v92, v92, v108
	v_mul_f32_e32 v93, v93, v109
	v_cvt_pk_bf16_f32 v90, v90, v91
	v_cvt_pk_bf16_f32 v91, v92, v93
	s_waitcnt vmcnt(0)
	v_sub_f32_e32 v94, v94, v32
	v_sub_f32_e32 v95, v95, v32
	v_sub_f32_e32 v96, v96, v32
	v_sub_f32_e32 v97, v97, v32
	v_mul_f32_e32 v94, v94, v33
	v_mul_f32_e32 v95, v95, v33
	v_mul_f32_e32 v96, v96, v33
	v_mul_f32_e32 v97, v97, v33
	v_fma_f32 v94, v94, v98, v102
	v_fma_f32 v95, v95, v99, v103
	v_fma_f32 v96, v96, v100, v104
	v_fma_f32 v97, v97, v101, v105
	v_mul_f32_e32 v106, 0xbfb8aa3b, v94
	v_mul_f32_e32 v107, 0xbfb8aa3b, v95
	v_mul_f32_e32 v108, 0xbfb8aa3b, v96
	v_mul_f32_e32 v109, 0xbfb8aa3b, v97
	v_exp_f32_e32 v106, v106
	v_exp_f32_e32 v107, v107
	v_exp_f32_e32 v108, v108
	v_exp_f32_e32 v109, v109
	v_add_f32_e32 v106, 1.0, v106
	v_add_f32_e32 v107, 1.0, v107
	v_add_f32_e32 v108, 1.0, v108
	v_add_f32_e32 v109, 1.0, v109
	v_rcp_f32_e32 v106, v106
	v_rcp_f32_e32 v107, v107
	v_rcp_f32_e32 v108, v108
	v_rcp_f32_e32 v109, v109
	v_mul_f32_e32 v94, v94, v106
	v_mul_f32_e32 v95, v95, v107
	v_mul_f32_e32 v96, v96, v108
	v_mul_f32_e32 v97, v97, v109
	v_cvt_pk_bf16_f32 v94, v94, v95
	v_cvt_pk_bf16_f32 v95, v96, v97
	global_store_dwordx2 v117, v[34:35], s[22:23] offset:2048
	s_add_u32 s22, s22, 0x1080
	s_addc_u32 s23, s23, 0
	global_store_dwordx2 v117, v[38:39], s[22:23] offset:2048
	s_add_u32 s22, s22, 0x1080
	s_addc_u32 s23, s23, 0
	global_store_dwordx2 v117, v[42:43], s[22:23] offset:2048
	s_add_u32 s22, s22, 0x1080
	s_addc_u32 s23, s23, 0
	global_store_dwordx2 v117, v[46:47], s[22:23] offset:2048
	s_add_u32 s22, s22, 0x1080
	s_addc_u32 s23, s23, 0
	global_store_dwordx2 v117, v[50:51], s[22:23] offset:2048
	s_add_u32 s22, s22, 0x1080
	s_addc_u32 s23, s23, 0
	global_store_dwordx2 v117, v[54:55], s[22:23] offset:2048
	s_add_u32 s22, s22, 0x1080
	s_addc_u32 s23, s23, 0
	global_store_dwordx2 v117, v[58:59], s[22:23] offset:2048
	s_add_u32 s22, s22, 0x1080
	s_addc_u32 s23, s23, 0
	global_store_dwordx2 v117, v[62:63], s[22:23] offset:2048
	s_add_u32 s22, s22, 0x1080
	s_addc_u32 s23, s23, 0
	global_store_dwordx2 v117, v[66:67], s[22:23] offset:2048
	s_add_u32 s22, s22, 0x1080
	s_addc_u32 s23, s23, 0
	global_store_dwordx2 v117, v[70:71], s[22:23] offset:2048
	s_add_u32 s22, s22, 0x1080
	s_addc_u32 s23, s23, 0
	global_store_dwordx2 v117, v[74:75], s[22:23] offset:2048
	s_add_u32 s22, s22, 0x1080
	s_addc_u32 s23, s23, 0
	global_store_dwordx2 v117, v[78:79], s[22:23] offset:2048
	s_add_u32 s22, s22, 0x1080
	s_addc_u32 s23, s23, 0
	global_store_dwordx2 v117, v[82:83], s[22:23] offset:2048
	s_add_u32 s22, s22, 0x1080
	s_addc_u32 s23, s23, 0
	global_store_dwordx2 v117, v[86:87], s[22:23] offset:2048
	s_add_u32 s22, s22, 0x1080
	s_addc_u32 s23, s23, 0
	global_store_dwordx2 v117, v[90:91], s[22:23] offset:2048
	s_add_u32 s22, s22, 0x1080
	s_addc_u32 s23, s23, 0
	global_store_dwordx2 v117, v[94:95], s[22:23] offset:2048
	s_mov_b64 s[40:41], 0

.Lnsa_fast_m:
	s_sub_i32 s42, 0, s82
	v_sub_u32_e32 v80, s42, v188
	v_sub_u32_e32 v79, 0, v80
	v_lshl_add_u32 v192, v174, 4, v137
	v_lshl_add_u32 v193, v176, 4, v143
	v_lshl_add_u32 v208, v178, 4, v190
	v_cvt_f32_i32_e32 v80, v80
	v_mul_f32_e32 v78, 0x40faf232, v119
	v_add_u32_e32 v192, -16, v192
	v_add_u32_e32 v193, -16, v193
	v_add_u32_e32 v208, -16, v208
	v_fmaak_f32 v76, v78, v80, 0xc31cd760
	v_add_u32_e32 v81, v191, v180
	ds_read_b128 v[244:247], v81
	v_add_u32_e32 v118, v191, v181
	ds_read_b128 v[248:251], v118
	v_add_u32_e32 v135, v191, v182
	ds_read_b128 v[252:255], v135
	v_add_u32_e32 v211, v191, v183
	ds_read_b128 v[196:199], v211
	v_add_u32_e32 v80, v191, v184
	ds_read_b128 v[200:203], v80
	v_add_u32_e32 v81, v191, v185
	ds_read_b128 v[204:207], v81
	v_add_u32_e32 v118, v191, v186
	ds_read_b128 v[68:71], v118
	v_add_u32_e32 v135, v191, v187
	ds_read_b128 v[72:75], v135
	v_fmamk_f32 v77, v78, 0x42000000, v76
	v_cndmask_b32_e64 v76, v162, v76, s[40:41]
	v_cndmask_b32_e64 v77, v162, v77, s[40:41]
	v_subrev_u32_e32 v211, 0, v79
	v_subrev_u32_e32 v80, 1, v79
	v_subrev_u32_e32 v81, 2, v79
	v_subrev_u32_e32 v118, 3, v79
	v_cmp_gt_u32_e32 vcc, s31, v211
	v_cmp_gt_u32_e64 s[44:45], s31, v80
	v_cmp_gt_u32_e64 s[46:47], s31, v81
	v_cmp_gt_u32_e64 s[48:49], s31, v118
	v_mov_b32_e32 v212, v76
	v_fmamk_f32 v213, v78, 0x3f800000, v76
	v_fmamk_f32 v214, v78, 0x40000000, v76
	v_fmamk_f32 v215, v78, 0x40400000, v76
	v_cndmask_b32_e32 v212, v162, v212, vcc
	v_cndmask_b32_e64 v213, v162, v213, s[44:45]
	v_cndmask_b32_e64 v214, v162, v214, s[46:47]
	v_cndmask_b32_e64 v215, v162, v215, s[48:49]
	v_subrev_u32_e32 v135, 8, v79
	v_subrev_u32_e32 v211, 9, v79
	v_subrev_u32_e32 v80, 10, v79
	v_subrev_u32_e32 v81, 11, v79
	v_cmp_gt_u32_e32 vcc, s31, v135
	v_cmp_gt_u32_e64 s[44:45], s31, v211
	v_cmp_gt_u32_e64 s[46:47], s31, v80
	v_cmp_gt_u32_e64 s[48:49], s31, v81
	v_fmamk_f32 v216, v78, 0x41000000, v76
	v_fmamk_f32 v217, v78, 0x41100000, v76
	v_fmamk_f32 v218, v78, 0x41200000, v76
	v_fmamk_f32 v219, v78, 0x41300000, v76
	v_cndmask_b32_e32 v216, v162, v216, vcc
	v_cndmask_b32_e64 v217, v162, v217, s[44:45]
	v_cndmask_b32_e64 v218, v162, v218, s[46:47]
	v_cndmask_b32_e64 v219, v162, v219, s[48:49]
	v_subrev_u32_e32 v118, 16, v79
	v_subrev_u32_e32 v135, 17, v79
	v_subrev_u32_e32 v211, 18, v79
	v_subrev_u32_e32 v80, 19, v79
	v_cmp_gt_u32_e32 vcc, s31, v118
	v_cmp_gt_u32_e64 s[44:45], s31, v135
	v_cmp_gt_u32_e64 s[46:47], s31, v211
	v_cmp_gt_u32_e64 s[48:49], s31, v80
	v_fmamk_f32 v220, v78, 0x41800000, v76
	v_fmamk_f32 v221, v78, 0x41880000, v76
	v_fmamk_f32 v222, v78, 0x41900000, v76
	v_fmamk_f32 v223, v78, 0x41980000, v76
	v_cndmask_b32_e32 v220, v162, v220, vcc
	v_cndmask_b32_e64 v221, v162, v221, s[44:45]
	v_cndmask_b32_e64 v222, v162, v222, s[46:47]
	v_cndmask_b32_e64 v223, v162, v223, s[48:49]
	v_subrev_u32_e32 v81, 24, v79
	v_subrev_u32_e32 v118, 25, v79
	v_subrev_u32_e32 v135, 26, v79
	v_subrev_u32_e32 v211, 27, v79
	v_cmp_gt_u32_e32 vcc, s31, v81
	v_cmp_gt_u32_e64 s[44:45], s31, v118
	v_cmp_gt_u32_e64 s[46:47], s31, v135
	v_cmp_gt_u32_e64 s[48:49], s31, v211
	v_fmamk_f32 v224, v78, 0x41c00000, v76
	v_fmamk_f32 v225, v78, 0x41c80000, v76
	v_fmamk_f32 v226, v78, 0x41d00000, v76
	v_fmamk_f32 v227, v78, 0x41d80000, v76
	v_cndmask_b32_e32 v224, v162, v224, vcc
	v_cndmask_b32_e64 v225, v162, v225, s[44:45]
	v_cndmask_b32_e64 v226, v162, v226, s[46:47]
	v_cndmask_b32_e64 v227, v162, v227, s[48:49]
	s_waitcnt lgkmcnt(7)
	s_nop 0
	v_mfma_f32_32x32x16_bf16 v[212:227], v[244:247], v[82:85], v[212:227]
	v_add_u32_e32 v80, v191, v180
	ds_read_b128 v[244:247], v80 offset:8192
	v_subrev_u32_e32 v81, 32, v79
	v_subrev_u32_e32 v118, 33, v79
	v_subrev_u32_e32 v135, 34, v79
	v_subrev_u32_e32 v211, 35, v79
	v_cmp_gt_u32_e32 vcc, s31, v81
	v_cmp_gt_u32_e64 s[44:45], s31, v118
	v_cmp_gt_u32_e64 s[46:47], s31, v135
	v_cmp_gt_u32_e64 s[48:49], s31, v211
	v_mov_b32_e32 v228, v77
	v_fmamk_f32 v229, v78, 0x3f800000, v77
	v_fmamk_f32 v230, v78, 0x40000000, v77
	v_fmamk_f32 v231, v78, 0x40400000, v77
	v_cndmask_b32_e32 v228, v162, v228, vcc
	v_cndmask_b32_e64 v229, v162, v229, s[44:45]
	v_cndmask_b32_e64 v230, v162, v230, s[46:47]
	v_cndmask_b32_e64 v231, v162, v231, s[48:49]
	s_waitcnt lgkmcnt(7)
	v_mfma_f32_32x32x16_bf16 v[212:227], v[248:251], v[86:89], v[212:227]
	v_add_u32_e32 v80, v191, v181
	ds_read_b128 v[248:251], v80 offset:8192
	s_waitcnt lgkmcnt(7)
	v_mfma_f32_32x32x16_bf16 v[212:227], v[252:255], v[90:93], v[212:227]
	v_add_u32_e32 v81, v191, v182
	ds_read_b128 v[252:255], v81 offset:8192
	v_subrev_u32_e32 v118, 40, v79
	v_subrev_u32_e32 v135, 41, v79
	v_subrev_u32_e32 v211, 42, v79
	v_subrev_u32_e32 v80, 43, v79
	v_cmp_gt_u32_e32 vcc, s31, v118
	v_cmp_gt_u32_e64 s[44:45], s31, v135
	v_cmp_gt_u32_e64 s[46:47], s31, v211
	v_cmp_gt_u32_e64 s[48:49], s31, v80
	v_fmamk_f32 v232, v78, 0x41000000, v77
	v_fmamk_f32 v233, v78, 0x41100000, v77
	v_fmamk_f32 v234, v78, 0x41200000, v77
	v_fmamk_f32 v235, v78, 0x41300000, v77
	v_cndmask_b32_e32 v232, v162, v232, vcc
	v_cndmask_b32_e64 v233, v162, v233, s[44:45]
	v_cndmask_b32_e64 v234, v162, v234, s[46:47]
	v_cndmask_b32_e64 v235, v162, v235, s[48:49]
	s_waitcnt lgkmcnt(7)
	v_mfma_f32_32x32x16_bf16 v[212:227], v[196:199], v[94:97], v[212:227]
	v_add_u32_e32 v81, v191, v183
	ds_read_b128 v[196:199], v81 offset:8192
	s_waitcnt lgkmcnt(7)
	v_mfma_f32_32x32x16_bf16 v[212:227], v[200:203], v[98:101], v[212:227]
	v_add_u32_e32 v118, v191, v184
	ds_read_b128 v[200:203], v118 offset:8192
	v_subrev_u32_e32 v135, 48, v79
	v_subrev_u32_e32 v211, 49, v79
	v_subrev_u32_e32 v80, 50, v79
	v_subrev_u32_e32 v81, 51, v79
	v_cmp_gt_u32_e32 vcc, s31, v135
	v_cmp_gt_u32_e64 s[44:45], s31, v211
	v_cmp_gt_u32_e64 s[46:47], s31, v80
	v_cmp_gt_u32_e64 s[48:49], s31, v81
	v_fmamk_f32 v236, v78, 0x41800000, v77
	v_fmamk_f32 v237, v78, 0x41880000, v77
	v_fmamk_f32 v238, v78, 0x41900000, v77
	v_fmamk_f32 v239, v78, 0x41980000, v77
	v_cndmask_b32_e32 v236, v162, v236, vcc
	v_cndmask_b32_e64 v237, v162, v237, s[44:45]
	v_cndmask_b32_e64 v238, v162, v238, s[46:47]
	v_cndmask_b32_e64 v239, v162, v239, s[48:49]
	s_waitcnt lgkmcnt(7)
	v_mfma_f32_32x32x16_bf16 v[212:227], v[204:207], v[102:105], v[212:227]
	v_add_u32_e32 v118, v191, v185
	ds_read_b128 v[204:207], v118 offset:8192
	s_waitcnt lgkmcnt(7)
	v_mfma_f32_32x32x16_bf16 v[212:227], v[68:71], v[106:109], v[212:227]
	v_add_u32_e32 v135, v191, v186
	ds_read_b128 v[68:71], v135 offset:8192
	v_subrev_u32_e32 v211, 56, v79
	v_subrev_u32_e32 v80, 57, v79
	v_subrev_u32_e32 v81, 58, v79
	v_subrev_u32_e32 v118, 59, v79
	v_cmp_gt_u32_e32 vcc, s31, v211
	v_cmp_gt_u32_e64 s[44:45], s31, v80
	v_cmp_gt_u32_e64 s[46:47], s31, v81
	v_cmp_gt_u32_e64 s[48:49], s31, v118
	v_fmamk_f32 v240, v78, 0x41c00000, v77
	v_fmamk_f32 v241, v78, 0x41c80000, v77
	v_fmamk_f32 v242, v78, 0x41d00000, v77
	v_fmamk_f32 v243, v78, 0x41d80000, v77
	v_cndmask_b32_e32 v240, v162, v240, vcc
	v_cndmask_b32_e64 v241, v162, v241, s[44:45]
	v_cndmask_b32_e64 v242, v162, v242, s[46:47]
	v_cndmask_b32_e64 v243, v162, v243, s[48:49]
	s_waitcnt lgkmcnt(7)
	v_mfma_f32_32x32x16_bf16 v[212:227], v[72:75], v[110:113], v[212:227]
	v_add_u32_e32 v135, v191, v187
	ds_read_b128 v[72:75], v135 offset:8192
	s_waitcnt lgkmcnt(7)
	v_mfma_f32_32x32x16_bf16 v[228:243], v[244:247], v[82:85], v[228:243]
	ds_read_b64 v[244:245], v192 offset:16
	v_xor_b32_e32 v211, 16, v192
	ds_read_b64 v[246:247], v211 offset:16
	s_waitcnt lgkmcnt(8)
	v_mfma_f32_32x32x16_bf16 v[228:243], v[248:251], v[86:89], v[228:243]
	ds_read_b64 v[248:249], v193 offset:16
	v_xor_b32_e32 v80, 16, v193
	ds_read_b64 v[250:251], v80 offset:16
	s_waitcnt lgkmcnt(9)
	v_mfma_f32_32x32x16_bf16 v[228:243], v[252:255], v[90:93], v[228:243]
	ds_read_b64 v[252:253], v192 offset:8208
	v_xor_b32_e32 v81, 16, v192
	ds_read_b64 v[254:255], v81 offset:8208
	s_waitcnt lgkmcnt(10)
	v_mfma_f32_32x32x16_bf16 v[228:243], v[196:199], v[94:97], v[228:243]
	ds_read_b64 v[196:197], v208 offset:16
	v_xor_b32_e32 v118, 16, v208
	ds_read_b64 v[198:199], v118 offset:16
	v_mul_f32_e32 v212, s37, v212
	v_mul_f32_e32 v213, s37, v213
	v_mul_f32_e32 v214, s37, v214
	v_mul_f32_e32 v215, s37, v215
	v_mul_f32_e32 v216, s37, v216
	v_mul_f32_e32 v217, s37, v217
	s_waitcnt lgkmcnt(11)
	v_mfma_f32_32x32x16_bf16 v[228:243], v[200:203], v[98:101], v[228:243]
	v_xor_b32_e32 v135, 32, v192
	ds_read_b64 v[200:201], v135 offset:16
	v_xor_b32_e32 v211, 48, v192
	ds_read_b64 v[202:203], v211 offset:16
	v_mul_f32_e32 v218, s37, v218
	v_mul_f32_e32 v219, s37, v219
	v_exp_f32_e32 v212, v212
	v_exp_f32_e32 v213, v213
	v_exp_f32_e32 v214, v214
	v_exp_f32_e32 v215, v215
	s_waitcnt lgkmcnt(12)
	v_mfma_f32_32x32x16_bf16 v[228:243], v[204:207], v[102:105], v[228:243]
	v_xor_b32_e32 v80, 32, v193
	ds_read_b64 v[204:205], v80 offset:16
	v_xor_b32_e32 v81, 48, v193
	ds_read_b64 v[206:207], v81 offset:16
	v_exp_f32_e32 v216, v216
	v_exp_f32_e32 v217, v217
	v_exp_f32_e32 v218, v218
	v_exp_f32_e32 v219, v219
	v_add_f32_e32 v66, v66, v212
	v_add_f32_e32 v66, v66, v213
	s_waitcnt lgkmcnt(13)
	v_mfma_f32_32x32x16_bf16 v[228:243], v[68:71], v[106:109], v[228:243]
	v_xor_b32_e32 v118, 32, v192
	ds_read_b64 v[68:69], v118 offset:8208
	v_xor_b32_e32 v135, 48, v192
	ds_read_b64 v[70:71], v135 offset:8208
	v_cvt_pk_bf16_f32 v212, v212, v213
	v_add_f32_e32 v66, v66, v214
	v_add_f32_e32 v66, v66, v215
	v_cvt_pk_bf16_f32 v213, v214, v215
	v_add_f32_e32 v66, v66, v216
	v_add_f32_e32 v66, v66, v217
	s_waitcnt lgkmcnt(14)
	v_mfma_f32_32x32x16_bf16 v[228:243], v[72:75], v[110:113], v[228:243]
	v_xor_b32_e32 v211, 32, v208
	ds_read_b64 v[72:73], v211 offset:16
	v_xor_b32_e32 v80, 48, v208
	ds_read_b64 v[74:75], v80 offset:16
	v_cvt_pk_bf16_f32 v214, v216, v217
	v_add_f32_e32 v66, v66, v218
	v_add_f32_e32 v66, v66, v219
	v_cvt_pk_bf16_f32 v215, v218, v219
	s_waitcnt lgkmcnt(14)
	s_nop 0
	v_mfma_f32_32x32x16_bf16 v[50:65], v[244:247], v[212:215], v[50:65]
	v_xor_b32_e32 v81, 64, v192
	ds_read_b64 v[244:245], v81 offset:16
	v_xor_b32_e32 v118, 0x50, v192
	ds_read_b64 v[246:247], v118 offset:16
	v_mul_f32_e32 v220, s37, v220
	v_mul_f32_e32 v221, s37, v221
	v_mul_f32_e32 v222, s37, v222
	v_mul_f32_e32 v223, s37, v223
	v_mul_f32_e32 v224, s37, v224
	v_mul_f32_e32 v225, s37, v225
	v_mul_f32_e32 v226, s37, v226
	s_waitcnt lgkmcnt(14)
	v_mfma_f32_32x32x16_bf16 v[34:49], v[248:251], v[212:215], v[34:49]
	v_xor_b32_e32 v135, 64, v193
	ds_read_b64 v[248:249], v135 offset:16
	v_xor_b32_e32 v211, 0x50, v193
	ds_read_b64 v[250:251], v211 offset:16
	v_mul_f32_e32 v227, s37, v227
	v_exp_f32_e32 v220, v220
	v_exp_f32_e32 v221, v221
	v_exp_f32_e32 v222, v222
	v_exp_f32_e32 v223, v223
	v_exp_f32_e32 v224, v224
	v_exp_f32_e32 v225, v225
	s_waitcnt lgkmcnt(14)
	v_mfma_f32_32x32x16_bf16 v[18:33], v[252:255], v[212:215], v[18:33]
	v_xor_b32_e32 v80, 64, v192
	ds_read_b64 v[252:253], v80 offset:8208
	v_xor_b32_e32 v81, 0x50, v192
	ds_read_b64 v[254:255], v81 offset:8208
	v_exp_f32_e32 v226, v226
	v_exp_f32_e32 v227, v227
	v_add_f32_e32 v66, v66, v220
	v_add_f32_e32 v66, v66, v221
	v_cvt_pk_bf16_f32 v220, v220, v221
	v_add_f32_e32 v66, v66, v222
	v_add_f32_e32 v66, v66, v223
	s_waitcnt lgkmcnt(14)
	v_mfma_f32_32x32x16_bf16 v[2:17], v[196:199], v[212:215], v[2:17]
	v_xor_b32_e32 v118, 64, v208
	ds_read_b64 v[196:197], v118 offset:16
	v_xor_b32_e32 v135, 0x50, v208
	ds_read_b64 v[198:199], v135 offset:16
	v_cvt_pk_bf16_f32 v221, v222, v223
	v_add_f32_e32 v66, v66, v224
	v_add_f32_e32 v66, v66, v225
	v_cvt_pk_bf16_f32 v222, v224, v225
	v_add_f32_e32 v66, v66, v226
	v_add_f32_e32 v66, v66, v227
	v_cvt_pk_bf16_f32 v223, v226, v227
	s_waitcnt lgkmcnt(14)
	s_nop 0
	v_mfma_f32_32x32x16_bf16 v[50:65], v[200:203], v[220:223], v[50:65]
	v_xor_b32_e32 v211, 0x60, v192
	ds_read_b64 v[200:201], v211 offset:16
	v_xor_b32_e32 v80, 0x70, v192
	ds_read_b64 v[202:203], v80 offset:16
	v_mul_f32_e32 v228, s37, v228
	v_mul_f32_e32 v229, s37, v229
	v_mul_f32_e32 v230, s37, v230
	v_mul_f32_e32 v231, s37, v231
	v_mul_f32_e32 v232, s37, v232
	v_mul_f32_e32 v233, s37, v233
	v_mul_f32_e32 v234, s37, v234
	s_waitcnt lgkmcnt(14)
	v_mfma_f32_32x32x16_bf16 v[34:49], v[204:207], v[220:223], v[34:49]
	v_xor_b32_e32 v81, 0x60, v193
	ds_read_b64 v[204:205], v81 offset:16
	v_xor_b32_e32 v118, 0x70, v193
	ds_read_b64 v[206:207], v118 offset:16
	v_mul_f32_e32 v235, s37, v235
	v_exp_f32_e32 v228, v228
	v_exp_f32_e32 v229, v229
	v_exp_f32_e32 v230, v230
	v_exp_f32_e32 v231, v231
	v_exp_f32_e32 v232, v232
	v_exp_f32_e32 v233, v233
	s_waitcnt lgkmcnt(14)
	v_mfma_f32_32x32x16_bf16 v[18:33], v[68:71], v[220:223], v[18:33]
	v_xor_b32_e32 v135, 0x60, v192
	ds_read_b64 v[68:69], v135 offset:8208
	v_xor_b32_e32 v211, 0x70, v192
	ds_read_b64 v[70:71], v211 offset:8208
	v_exp_f32_e32 v234, v234
	v_exp_f32_e32 v235, v235
	v_add_f32_e32 v66, v66, v228
	v_add_f32_e32 v66, v66, v229
	v_cvt_pk_bf16_f32 v228, v228, v229
	v_add_f32_e32 v66, v66, v230
	v_add_f32_e32 v66, v66, v231
	s_waitcnt lgkmcnt(14)
	v_mfma_f32_32x32x16_bf16 v[2:17], v[72:75], v[220:223], v[2:17]
	v_xor_b32_e32 v80, 0x60, v208
	ds_read_b64 v[72:73], v80 offset:16
	v_xor_b32_e32 v81, 0x70, v208
	ds_read_b64 v[74:75], v81 offset:16
	v_cvt_pk_bf16_f32 v229, v230, v231
	v_add_f32_e32 v66, v66, v232
	v_add_f32_e32 v66, v66, v233
	v_cvt_pk_bf16_f32 v230, v232, v233
	v_add_f32_e32 v66, v66, v234
	v_add_f32_e32 v66, v66, v235
	v_cvt_pk_bf16_f32 v231, v234, v235
	s_waitcnt lgkmcnt(14)
	s_nop 0
	v_mfma_f32_32x32x16_bf16 v[50:65], v[244:247], v[228:231], v[50:65]
	v_mul_f32_e32 v236, s37, v236
	v_mul_f32_e32 v237, s37, v237
	v_mul_f32_e32 v238, s37, v238
	v_mul_f32_e32 v239, s37, v239
	v_mul_f32_e32 v240, s37, v240
	v_mul_f32_e32 v241, s37, v241
	v_mul_f32_e32 v242, s37, v242
	s_waitcnt lgkmcnt(12)
	v_mfma_f32_32x32x16_bf16 v[34:49], v[248:251], v[228:231], v[34:49]
	v_mul_f32_e32 v243, s37, v243
	v_exp_f32_e32 v236, v236
	v_exp_f32_e32 v237, v237
	v_exp_f32_e32 v238, v238
	v_exp_f32_e32 v239, v239
	v_exp_f32_e32 v240, v240
	v_exp_f32_e32 v241, v241
	s_waitcnt lgkmcnt(10)
	v_mfma_f32_32x32x16_bf16 v[18:33], v[252:255], v[228:231], v[18:33]
	v_exp_f32_e32 v242, v242
	v_exp_f32_e32 v243, v243
	v_add_f32_e32 v66, v66, v236
	v_add_f32_e32 v66, v66, v237
	v_cvt_pk_bf16_f32 v236, v236, v237
	v_add_f32_e32 v66, v66, v238
	v_add_f32_e32 v66, v66, v239
	s_waitcnt lgkmcnt(8)
	v_mfma_f32_32x32x16_bf16 v[2:17], v[196:199], v[228:231], v[2:17]
	v_cvt_pk_bf16_f32 v237, v238, v239
	v_add_f32_e32 v66, v66, v240
	v_add_f32_e32 v66, v66, v241
	v_cvt_pk_bf16_f32 v238, v240, v241
	v_add_f32_e32 v66, v66, v242
	v_add_f32_e32 v66, v66, v243
	v_cvt_pk_bf16_f32 v239, v242, v243
	s_waitcnt lgkmcnt(6)
	s_nop 0
	v_mfma_f32_32x32x16_bf16 v[50:65], v[200:203], v[236:239], v[50:65]
	s_waitcnt lgkmcnt(4)
	v_mfma_f32_32x32x16_bf16 v[34:49], v[204:207], v[236:239], v[34:49]
	s_waitcnt lgkmcnt(2)
	v_mfma_f32_32x32x16_bf16 v[18:33], v[68:71], v[236:239], v[18:33]
	s_waitcnt lgkmcnt(0)
	v_mfma_f32_32x32x16_bf16 v[2:17], v[72:75], v[236:239], v[2:17]
	s_branch .LBB0_323

.LBB0_323:
	s_cmp_lg_u32 s29, s95
	s_cbranch_scc1 .LBB0_325
	ds_bpermute_b32 v67, v172, v66
	global_load_dword v68, v[124:125], off offset:4
	global_load_ushort v69, v[120:121], off offset:2
	global_load_dwordx4 v[212:215], v[122:123], off
	global_load_dwordx4 v[216:219], v[122:123], off offset:32
	global_load_dwordx4 v[220:223], v[122:123], off offset:64
	global_load_dwordx4 v[224:227], v[122:123], off offset:96
	global_load_dwordx4 v[228:231], v[122:123], off offset:128
	global_load_dwordx4 v[232:235], v[122:123], off offset:160
	global_load_dwordx4 v[236:239], v[122:123], off offset:192
	global_load_dwordx4 v[240:243], v[122:123], off offset:224
	global_load_dwordx4 v[244:247], v[122:123], off offset:256
	global_load_dwordx4 v[248:251], v[122:123], off offset:288
	global_load_dwordx4 v[252:255], v[122:123], off offset:320
	global_load_dwordx4 v[196:199], v[122:123], off offset:352
	global_load_dwordx4 v[200:203], v[122:123], off offset:384
	global_load_dwordx4 v[204:207], v[122:123], off offset:416
	global_load_dwordx4 v[72:75], v[122:123], off offset:448
	global_load_dwordx4 v[76:79], v[122:123], off offset:480
	s_waitcnt lgkmcnt(0)
	v_add_f32_e32 v66, v66, v67
	v_cmp_lt_f32_e32 vcc, 0, v66
	v_rcp_f32_e32 v66, v66
	s_waitcnt vmcnt(16)
	v_lshlrev_b32_e32 v67, 16, v69
	v_add_f32_e32 v67, v68, v67
	v_mul_f32_e32 v67, 0xbfb8aa3b, v67
	v_exp_f32_e32 v67, v67
	v_cndmask_b32_e32 v66, 0, v66, vcc
	v_add_f32_e32 v67, 1.0, v67
	v_rcp_f32_e32 v67, v67
	s_nop 0
	v_mul_f32_e32 v66, v66, v67
	s_waitcnt vmcnt(15)
	v_pk_fma_f32 v[212:213], v[50:51], v[66:67], v[212:213] op_sel_hi:[1,0,1]
	v_pk_fma_f32 v[214:215], v[52:53], v[66:67], v[214:215] op_sel_hi:[1,0,1]
	s_waitcnt vmcnt(14)
	v_pk_fma_f32 v[216:217], v[54:55], v[66:67], v[216:217] op_sel_hi:[1,0,1]
	v_pk_fma_f32 v[218:219], v[56:57], v[66:67], v[218:219] op_sel_hi:[1,0,1]
	s_waitcnt vmcnt(13)
	v_pk_fma_f32 v[220:221], v[58:59], v[66:67], v[220:221] op_sel_hi:[1,0,1]
	v_pk_fma_f32 v[222:223], v[60:61], v[66:67], v[222:223] op_sel_hi:[1,0,1]
	s_waitcnt vmcnt(12)
	v_pk_fma_f32 v[224:225], v[62:63], v[66:67], v[224:225] op_sel_hi:[1,0,1]
	v_pk_fma_f32 v[226:227], v[64:65], v[66:67], v[226:227] op_sel_hi:[1,0,1]
	s_waitcnt vmcnt(11)
	v_pk_fma_f32 v[228:229], v[34:35], v[66:67], v[228:229] op_sel_hi:[1,0,1]
	v_pk_fma_f32 v[230:231], v[36:37], v[66:67], v[230:231] op_sel_hi:[1,0,1]
	s_waitcnt vmcnt(10)
	v_pk_fma_f32 v[232:233], v[38:39], v[66:67], v[232:233] op_sel_hi:[1,0,1]
	v_pk_fma_f32 v[234:235], v[40:41], v[66:67], v[234:235] op_sel_hi:[1,0,1]
	s_waitcnt vmcnt(9)
	v_pk_fma_f32 v[236:237], v[42:43], v[66:67], v[236:237] op_sel_hi:[1,0,1]
	v_pk_fma_f32 v[238:239], v[44:45], v[66:67], v[238:239] op_sel_hi:[1,0,1]
	s_waitcnt vmcnt(8)
	v_pk_fma_f32 v[240:241], v[46:47], v[66:67], v[240:241] op_sel_hi:[1,0,1]
	v_pk_fma_f32 v[242:243], v[48:49], v[66:67], v[242:243] op_sel_hi:[1,0,1]
	s_waitcnt vmcnt(7)
	v_pk_fma_f32 v[244:245], v[18:19], v[66:67], v[244:245] op_sel_hi:[1,0,1]
	v_pk_fma_f32 v[246:247], v[20:21], v[66:67], v[246:247] op_sel_hi:[1,0,1]
	s_waitcnt vmcnt(6)
	v_pk_fma_f32 v[248:249], v[22:23], v[66:67], v[248:249] op_sel_hi:[1,0,1]
	v_pk_fma_f32 v[250:251], v[24:25], v[66:67], v[250:251] op_sel_hi:[1,0,1]
	s_waitcnt vmcnt(5)
	v_pk_fma_f32 v[252:253], v[26:27], v[66:67], v[252:253] op_sel_hi:[1,0,1]
	v_pk_fma_f32 v[254:255], v[28:29], v[66:67], v[254:255] op_sel_hi:[1,0,1]
	s_waitcnt vmcnt(4)
	v_pk_fma_f32 v[196:197], v[30:31], v[66:67], v[196:197] op_sel_hi:[1,0,1]
	v_pk_fma_f32 v[198:199], v[32:33], v[66:67], v[198:199] op_sel_hi:[1,0,1]
	s_waitcnt vmcnt(3)
	v_pk_fma_f32 v[200:201], v[2:3], v[66:67], v[200:201] op_sel_hi:[1,0,1]
	v_pk_fma_f32 v[202:203], v[4:5], v[66:67], v[202:203] op_sel_hi:[1,0,1]
	s_waitcnt vmcnt(2)
	v_pk_fma_f32 v[204:205], v[6:7], v[66:67], v[204:205] op_sel_hi:[1,0,1]
	v_pk_fma_f32 v[206:207], v[8:9], v[66:67], v[206:207] op_sel_hi:[1,0,1]
	s_waitcnt vmcnt(1)
	v_pk_fma_f32 v[72:73], v[10:11], v[66:67], v[72:73] op_sel_hi:[1,0,1]
	v_pk_fma_f32 v[74:75], v[12:13], v[66:67], v[74:75] op_sel_hi:[1,0,1]
	s_waitcnt vmcnt(0)
	v_pk_fma_f32 v[76:77], v[14:15], v[66:67], v[76:77] op_sel_hi:[1,0,1]
	v_pk_fma_f32 v[78:79], v[16:17], v[66:67], v[78:79] op_sel_hi:[1,0,1]
	global_store_dwordx4 v[122:123], v[212:215], off
	global_store_dwordx4 v[122:123], v[216:219], off offset:32
	global_store_dwordx4 v[122:123], v[220:223], off offset:64
	global_store_dwordx4 v[122:123], v[224:227], off offset:96
	global_store_dwordx4 v[122:123], v[228:231], off offset:128
	global_store_dwordx4 v[122:123], v[232:235], off offset:160
	global_store_dwordx4 v[122:123], v[236:239], off offset:192
	global_store_dwordx4 v[122:123], v[240:243], off offset:224
	global_store_dwordx4 v[122:123], v[244:247], off offset:256
	global_store_dwordx4 v[122:123], v[248:251], off offset:288
	global_store_dwordx4 v[122:123], v[252:255], off offset:320
	global_store_dwordx4 v[122:123], v[196:199], off offset:352
	global_store_dwordx4 v[122:123], v[200:203], off offset:384
	global_store_dwordx4 v[122:123], v[204:207], off offset:416
	global_store_dwordx4 v[122:123], v[72:75], off offset:448
	global_store_dwordx4 v[122:123], v[76:79], off offset:480
	v_mov_b32_e32 v16, v1
	v_mov_b32_e32 v17, v1
	v_mov_b32_e32 v2, v1
	v_mov_b32_e32 v3, v1
	v_mov_b32_e32 v4, v1
	v_mov_b32_e32 v5, v1
	v_mov_b32_e32 v6, v1
	v_mov_b32_e32 v7, v1
	v_mov_b32_e32 v8, v1
	v_mov_b32_e32 v9, v1
	v_mov_b32_e32 v10, v1
	v_mov_b32_e32 v11, v1
	v_mov_b32_e32 v12, v1
	v_mov_b32_e32 v13, v1
	v_mov_b32_e32 v14, v1
	v_mov_b32_e32 v15, v1
	v_mov_b64_e32 v[32:33], v[16:17]
	v_mov_b64_e32 v[48:49], v[16:17]
	v_mov_b64_e32 v[64:65], v[16:17]
	v_mov_b32_e32 v66, 0
	v_mov_b32_e32 v67, 0x41a00000
	v_mov_b64_e32 v[30:31], v[14:15]
	v_mov_b64_e32 v[28:29], v[12:13]
	v_mov_b64_e32 v[26:27], v[10:11]
	v_mov_b64_e32 v[24:25], v[8:9]
	v_mov_b64_e32 v[22:23], v[6:7]
	v_mov_b64_e32 v[20:21], v[4:5]
	v_mov_b64_e32 v[18:19], v[2:3]
	v_mov_b64_e32 v[46:47], v[14:15]
	v_mov_b64_e32 v[44:45], v[12:13]
	v_mov_b64_e32 v[42:43], v[10:11]
	v_mov_b64_e32 v[40:41], v[8:9]
	v_mov_b64_e32 v[38:39], v[6:7]
	v_mov_b64_e32 v[36:37], v[4:5]
	v_mov_b64_e32 v[34:35], v[2:3]
	v_mov_b64_e32 v[62:63], v[14:15]
	v_mov_b64_e32 v[60:61], v[12:13]
	v_mov_b64_e32 v[58:59], v[10:11]
	v_mov_b64_e32 v[56:57], v[8:9]
	v_mov_b64_e32 v[54:55], v[6:7]
	v_mov_b64_e32 v[52:53], v[4:5]
	v_mov_b64_e32 v[50:51], v[2:3]
